# attn_d: second-round units remapped (unit ^ 0x7f) to pair expensive and cheap (head, query-block) units per workgroup
# baseline (speedup 1.0000x reference)
.LBB0_610:
	s_xor_b32 s20, s23, 0x7f
	s_cmpk_lt_i32 s23, 0x100
	s_cselect_b32 s20, s23, s20
	s_ashr_i32 s5, s20, 7
	s_bfe_u32 s4, s20, 0x20005
	s_mul_hi_i32 s8, s5, 0x3e00000
	s_mul_i32 s5, s5, 0x3e00000
	s_add_u32 s18, s2, s5
	s_addc_u32 s19, s17, s8
	s_lshl_b32 s5, s20, 7
	s_and_b32 s5, s5, 0xf80
	v_and_b32_e32 v64, 15, v2
	v_lshl_add_u32 v0, v3, 4, s5
	v_or_b32_e32 v66, v0, v64
	v_mov_b64_e32 v[20:21], s[18:19]
	v_mad_i64_i32 v[4:5], s[18:19], v66, s65, v[20:21]
	s_lshl_b32 s8, s4, 8
	v_bfe_u32 v65, v2, 4, 2
	v_lshl_add_u64 v[4:5], v[4:5], 0, s[8:9]
	s_mov_b64 s[18:19], 0x2200
	v_lshl_add_u64 v[132:133], v[4:5], 0, s[18:19]
	v_lshlrev_b32_e32 v0, 4, v65
	v_lshl_add_u64 v[16:17], v[132:133], 0, v[0:1]
	v_ashrrev_i32_e32 v67, 4, v2
	global_load_dwordx4 v[4:7], v[16:17], off
	global_load_dwordx4 v[8:11], v[16:17], off offset:64
	global_load_dwordx4 v[12:15], v[16:17], off offset:128
	s_nop 0
	global_load_dwordx4 v[16:19], v[16:17], off offset:192
	v_lshlrev_b32_e32 v0, 4, v2
	v_mad_i64_i32 v[20:21], s[18:19], v67, s65, v[20:21]
	v_lshl_add_u64 v[20:21], v[20:21], 0, s[8:9]
	v_and_b32_e32 v0, 0xf0, v0
	v_lshl_add_u64 v[36:37], v[20:21], 0, v[0:1]
	v_add_co_u32_e32 v24, vcc, s64, v36
	s_mov_b32 s5, 0x7e000
	s_nop 0
	v_addc_co_u32_e32 v25, vcc, 0, v37, vcc
	v_add_co_u32_e32 v32, vcc, s5, v36
	s_mov_b64 s[18:19], 0x2600
	s_waitcnt lgkmcnt(0)
	v_addc_co_u32_e32 v33, vcc, 0, v37, vcc
	global_load_dwordx4 v[20:23], v[24:25], off offset:1536
	s_nop 0
	global_load_dwordx4 v[24:27], v[24:25], off offset:2560
	s_nop 0
	global_load_dwordx4 v[28:31], v[32:33], off offset:1536
	s_nop 0
	global_load_dwordx4 v[32:35], v[32:33], off offset:2560
	v_lshl_add_u64 v[134:135], v[36:37], 0, s[18:19]
	s_mov_b64 s[18:19], 0x2a00
	v_lshl_add_u64 v[136:137], v[36:37], 0, s[18:19]
	v_mul_lo_u32 v36, v67, s21
	v_add3_u32 v169, 0, v0, v36
	v_lshlrev_b32_e32 v167, 2, v65
	s_barrier
	s_not_b32 s4, s4
	s_lshl_b32 s4, s4, 1
	v_ldexp_f32 v0, 1.0, s4
	v_lshlrev_b32_e32 v68, 3, v65
	v_mul_f32_e32 v150, 0x3fb8aa3b, v0
	v_readfirstlane_b32 s4, v3
	v_mul_u32_u24_e32 v0, 0x90, v64
	s_cmp_gt_i32 s4, 3
	s_mov_b64 s[4:5], -1
	v_lshlrev_b32_e32 v171, 1, v0
	v_lshlrev_b32_e32 v172, 1, v68
	s_waitcnt vmcnt(3)
	ds_write_b128 v169, v[20:23]
	s_waitcnt vmcnt(2)
	ds_write_b128 v169, v[24:27] offset:36864
	s_waitcnt vmcnt(1)
	ds_write_b128 v169, v[28:31] offset:9216
	s_waitcnt vmcnt(0)
	ds_write_b128 v169, v[32:35] offset:46080
	v_lshlrev_b32_e32 v38, 16, v4
	v_and_b32_e32 v39, 0xffff0000, v4
	v_lshlrev_b32_e32 v4, 16, v5
	v_and_b32_e32 v5, 0xffff0000, v5
	v_lshlrev_b32_e32 v50, 16, v16
	v_and_b32_e32 v51, 0xffff0000, v16
	v_pk_mul_f32 v[38:39], v[38:39], s[16:17] op_sel_hi:[1,0]
	v_pk_mul_f32 v[52:53], v[4:5], s[16:17] op_sel_hi:[1,0]
	v_cvt_pk_bf16_f32 v4, v38, v39
	v_pk_mul_f32 v[38:39], v[50:51], s[16:17] op_sel_hi:[1,0]
	v_sub_u32_e32 v20, v167, v66
	v_cvt_pk_bf16_f32 v16, v38, v39
	v_lshlrev_b32_e32 v38, 16, v17
	v_and_b32_e32 v39, 0xffff0000, v17
	v_pk_mul_f32 v[38:39], v[38:39], s[16:17] op_sel_hi:[1,0]
	v_cvt_f32_i32_e32 v170, v20
	v_cvt_pk_bf16_f32 v17, v38, v39
	v_lshlrev_b32_e32 v38, 16, v18
	v_and_b32_e32 v39, 0xffff0000, v18
	v_pk_mul_f32 v[38:39], v[38:39], s[16:17] op_sel_hi:[1,0]
	v_lshlrev_b32_e32 v40, 16, v6
	v_cvt_pk_bf16_f32 v18, v38, v39
	v_lshlrev_b32_e32 v38, 16, v19
	v_and_b32_e32 v39, 0xffff0000, v19
	v_pk_mul_f32 v[38:39], v[38:39], s[16:17] op_sel_hi:[1,0]
	v_and_b32_e32 v41, 0xffff0000, v6
	v_cvt_pk_bf16_f32 v19, v38, v39
	v_lshlrev_b32_e32 v38, 3, v2
	v_bfe_u32 v2, v2, 2, 2
	v_lshlrev_b32_e32 v6, 16, v7
	v_and_b32_e32 v7, 0xffff0000, v7
	v_lshlrev_b32_e32 v42, 16, v8
	v_and_b32_e32 v43, 0xffff0000, v8
	v_lshlrev_b32_e32 v8, 16, v9
	v_and_b32_e32 v9, 0xffff0000, v9
	v_lshlrev_b32_e32 v44, 16, v10
	v_and_b32_e32 v45, 0xffff0000, v10
	v_lshlrev_b32_e32 v10, 16, v11
	v_and_b32_e32 v11, 0xffff0000, v11
	v_lshlrev_b32_e32 v46, 16, v12
	v_and_b32_e32 v47, 0xffff0000, v12
	v_lshlrev_b32_e32 v12, 16, v13
	v_and_b32_e32 v13, 0xffff0000, v13
	v_lshlrev_b32_e32 v48, 16, v14
	v_and_b32_e32 v49, 0xffff0000, v14
	v_lshlrev_b32_e32 v14, 16, v15
	v_and_b32_e32 v15, 0xffff0000, v15
	v_or_b32_e32 v2, v167, v2
	v_pk_mul_f32 v[40:41], v[40:41], s[16:17] op_sel_hi:[1,0]
	v_pk_mul_f32 v[54:55], v[6:7], s[16:17] op_sel_hi:[1,0]
	v_pk_mul_f32 v[42:43], v[42:43], s[16:17] op_sel_hi:[1,0]
	v_pk_mul_f32 v[56:57], v[8:9], s[16:17] op_sel_hi:[1,0]
	v_pk_mul_f32 v[44:45], v[44:45], s[16:17] op_sel_hi:[1,0]
	v_pk_mul_f32 v[58:59], v[10:11], s[16:17] op_sel_hi:[1,0]
	v_pk_mul_f32 v[46:47], v[46:47], s[16:17] op_sel_hi:[1,0]
	v_pk_mul_f32 v[60:61], v[12:13], s[16:17] op_sel_hi:[1,0]
	v_pk_mul_f32 v[48:49], v[48:49], s[16:17] op_sel_hi:[1,0]
	v_pk_mul_f32 v[62:63], v[14:15], s[16:17] op_sel_hi:[1,0]
	v_and_b32_e32 v3, 24, v38
	v_mad_u32_u24 v2, v2, s21, 0
	v_cvt_pk_bf16_f32 v5, v52, v53
	v_cvt_pk_bf16_f32 v6, v40, v41
	v_cvt_pk_bf16_f32 v7, v54, v55
	v_cvt_pk_bf16_f32 v8, v42, v43
	v_cvt_pk_bf16_f32 v9, v56, v57
	v_cvt_pk_bf16_f32 v10, v44, v45
	v_cvt_pk_bf16_f32 v11, v58, v59
	v_cvt_pk_bf16_f32 v12, v46, v47
	v_cvt_pk_bf16_f32 v13, v60, v61
	v_cvt_pk_bf16_f32 v14, v48, v49
	v_cvt_pk_bf16_f32 v15, v62, v63
	v_add_u32_e32 v168, v2, v3
	s_waitcnt lgkmcnt(0)
	s_barrier
	s_cbranch_scc0 .Ld_groupA
	v_mov_b32_e32 v28, 0
	v_mov_b32_e32 v29, 0
	v_mov_b32_e32 v30, 0
	v_mov_b32_e32 v31, 0
	v_mov_b32_e32 v32, 0
	v_mov_b32_e32 v33, 0
	v_mov_b32_e32 v34, 0
	v_mov_b32_e32 v35, 0
	v_mov_b32_e32 v40, 0
	v_mov_b32_e32 v41, 0
	v_mov_b32_e32 v42, 0
	v_mov_b32_e32 v43, 0
	v_mov_b32_e32 v52, 0
	v_mov_b32_e32 v53, 0
	v_mov_b32_e32 v54, 0
	v_mov_b32_e32 v55, 0
	v_mov_b32_e32 v56, 0
	v_mov_b32_e32 v57, 0
	v_mov_b32_e32 v58, 0
	v_mov_b32_e32 v59, 0
	v_mov_b32_e32 v64, 0
	v_mov_b32_e32 v65, 0
	v_mov_b32_e32 v66, 0
	v_mov_b32_e32 v67, 0
	v_mov_b32_e32 v72, 0
	v_mov_b32_e32 v73, 0
	v_mov_b32_e32 v74, 0
	v_mov_b32_e32 v75, 0
	v_mov_b32_e32 v84, 0
	v_mov_b32_e32 v85, 0
	v_mov_b32_e32 v86, 0
	v_mov_b32_e32 v87, 0
	v_mov_b32_e32 v36, 0
	v_mov_b32_e32 v37, 0
	v_mov_b32_e32 v38, 0
	v_mov_b32_e32 v39, 0
	v_mov_b32_e32 v44, 0
	v_mov_b32_e32 v45, 0
	v_mov_b32_e32 v46, 0
	v_mov_b32_e32 v47, 0
	v_mov_b32_e32 v48, 0
	v_mov_b32_e32 v49, 0
	v_mov_b32_e32 v50, 0
	v_mov_b32_e32 v51, 0
	v_mov_b32_e32 v60, 0
	v_mov_b32_e32 v61, 0
	v_mov_b32_e32 v62, 0
	v_mov_b32_e32 v63, 0
	v_mov_b32_e32 v68, 0
	v_mov_b32_e32 v69, 0
	v_mov_b32_e32 v70, 0
	v_mov_b32_e32 v71, 0
	v_mov_b32_e32 v76, 0
	v_mov_b32_e32 v77, 0
	v_mov_b32_e32 v78, 0
	v_mov_b32_e32 v79, 0
	v_mov_b32_e32 v80, 0
	v_mov_b32_e32 v81, 0
	v_mov_b32_e32 v82, 0
	v_mov_b32_e32 v83, 0
	v_mov_b32_e32 v20, 0
	v_mov_b32_e32 v21, 0
	v_mov_b32_e32 v22, 0
	v_mov_b32_e32 v23, 0
	v_mov_b32_e32 v120, 0
	v_mov_b32_e32 v121, 0
	v_mov_b32_e32 v122, 0
	v_mov_b32_e32 v123, 0
	v_mov_b32_e32 v124, 0
	v_mov_b32_e32 v125, 0
	v_mov_b32_e32 v126, 0
	v_mov_b32_e32 v127, 0
	v_mov_b32_e32 v128, 0
	v_mov_b32_e32 v129, 0
	v_mov_b32_e32 v130, 0
	v_mov_b32_e32 v131, 0
	v_mov_b32_e32 v152, 0
	v_mov_b32_e32 v153, 0
	v_mov_b32_e32 v154, 0
	v_mov_b32_e32 v155, 0
	v_mov_b32_e32 v0, 0
	v_mov_b32_e32 v151, 0
	v_mov_b32_e32 v24, 0
	v_mov_b32_e32 v25, 0
	s_mov_b32 s66, 0xff800000
	v_add_u32_e32 v255, v171, v172
	v_mov_b32_e32 v165, v170
	s_mov_b32 s5, 0
	s_mov_b32 s31, 0
	s_mov_b32 s38, 0
	s_mov_b32 s39, 0x4800
	s_mov_b32 s30, 0xf8000
	v_mov_b32_e32 v88, 0xff800000
	v_mov_b32_e32 v89, 0xff800000
	v_mov_b32_e32 v90, 0xff800000
	v_mov_b32_e32 v91, 0xff800000
	v_mov_b32_e32 v92, 0xff800000
	v_mov_b32_e32 v93, 0xff800000
	v_mov_b32_e32 v94, 0xff800000
	v_mov_b32_e32 v95, 0xff800000
	v_mov_b32_e32 v96, 0xff800000
	v_mov_b32_e32 v97, 0xff800000
	v_mov_b32_e32 v98, 0xff800000
	v_mov_b32_e32 v99, 0xff800000
	v_mov_b32_e32 v100, 0xff800000
	v_mov_b32_e32 v101, 0xff800000
	v_mov_b32_e32 v102, 0xff800000
	v_mov_b32_e32 v103, 0xff800000
	v_mov_b32_e32 v104, 0xff800000
	v_mov_b32_e32 v105, 0xff800000
	v_mov_b32_e32 v106, 0xff800000
	v_mov_b32_e32 v107, 0xff800000
	v_mov_b32_e32 v108, 0xff800000
	v_mov_b32_e32 v109, 0xff800000
	v_mov_b32_e32 v110, 0xff800000
	v_mov_b32_e32 v111, 0xff800000
	v_mov_b32_e32 v112, 0xff800000
	v_mov_b32_e32 v113, 0xff800000
	v_mov_b32_e32 v114, 0xff800000
	v_mov_b32_e32 v115, 0xff800000
	v_mov_b32_e32 v116, 0xff800000
	v_mov_b32_e32 v117, 0xff800000
	v_mov_b32_e32 v118, 0xff800000
	v_mov_b32_e32 v119, 0xff800000
